# three P1 conversion classes, fractions 1/8 first, 1/8 between the GEMM1 calls, 6/8 after
# baseline (speedup 1.0000x reference)
_Z3fwd4Args:
	v_writelane_b32 v249, s0, 0
	v_writelane_b32 v249, s1, 1
	v_writelane_b32 v249, s2, 2
	v_mov_b32_e32 v250, v0
	s_and_b32 s98, s2, 7
	s_movk_i32 s101, 0x100
	s_cmp_lt_u32 s98, 2
	s_cselect_b32 s101, 0x400, s101
	s_cmp_lt_u32 s98, 1
	s_cselect_b32 s101, 0, s101
